# attn loop: 5-tuple LDS fragment ring (v244-247 rematerialised at phase exit) so the last PV group's V reads issue one MFMA earlier before the mid-PV barrier; 5 K fragments prefetched across the barrie
# speedup vs baseline: 1.0130x; 1.0130x over previous
; __device__ __forceinline__ void partialSM(f32x16& p0, f32x16& p1, float& m_reg, float& mn, float& alpha) {
;     ...
;   for (int r = 0; r < 16; ++r) p0[r] = __builtin_amdgcn_exp2f(p0[r]);
; }
; __device__ __forceinline__ void finishSM(f32x16& p0, f32x16& p1, float alpha, float& l_reg, bf16x8& pa0, bf16x8& pa1, bf16x8& pa2, bf16x8& pa3) {
; #pragma unroll
;   for (int r = 0; r < 16; ++r) p1[r] = __builtin_amdgcn_exp2f(p1[r]);
;   float ps = 0;
; #pragma unroll
;   for (int r = 0; r < 16; ++r) ps += p0[r];
; #pragma unroll
;   for (int r = 0; r < 16; ++r) ps += p1[r];
;   { auto rr = __builtin_amdgcn_permlane32_swap(__float_as_uint(ps), __float_as_uint(ps), false, false);
;     ps = __uint_as_float(rr[0]) + __uint_as_float(rr[1]); }
;   l_reg = l_reg * alpha + ps;
;     ...
;   PK4(p0, 0, pa0); PK4(p0, 8, pa1); PK4(p1, 0, pa2); PK4(p1, 8, pa3);
;     ...
; }
; __device__ __forceinline__ void qkt(f32x16& p0, f32x16& p1, const char* Ks, const bf16x8* qr, const char* qrl, int r32, int hi) {
;   p0 = f32x16{}; p1 = f32x16{};
; #pragma unroll
;   for (int d0 = 0; d0 < 8; ++d0) { int cb = (d0 * 16 + hi * 8) * 2;
;     bf16x8 b0 = *reinterpret_cast<const bf16x8*>(Ks + KSWZ(r32, cb));
;     bf16x8 b1 = *reinterpret_cast<const bf16x8*>(Ks + KSWZ(32 + r32, cb));
;     p0 = __builtin_amdgcn_mfma_f32_32x32x16_bf16(b0, qr[d0], p0, 0, 0, 0);
;     p1 = __builtin_amdgcn_mfma_f32_32x32x16_bf16(b1, qr[d0], p1, 0, 0, 0); }
; #pragma unroll
;   for (int d0 = 8; d0 < 12; ++d0) { int cb = (d0 * 16 + hi * 8) * 2;
;     bf16x8 b0 = *reinterpret_cast<const bf16x8*>(Ks + KSWZ(r32, cb));
;     bf16x8 b1 = *reinterpret_cast<const bf16x8*>(Ks + KSWZ(32 + r32, cb));
;     bf16x8 qf = *reinterpret_cast<const bf16x8*>(qrl + (((2 * (d0 - 8) + hi) ^ ((r32 >> 1) & 7)) << 4));
;     p0 = __builtin_amdgcn_mfma_f32_32x32x16_bf16(b0, qf, p0, 0, 0, 0);
;     p1 = __builtin_amdgcn_mfma_f32_32x32x16_bf16(b1, qf, p1, 0, 0, 0); }
; }
.LBB0_1151:
	s_sub_i32 s30, s76, 1
	s_cmp_eq_u32 s76, 0
	s_cselect_b32 s30, 2, s30
	s_add_i32 s18, s76, 1
	s_cmp_lg_u32 s76, 2
	s_cselect_b32 s18, s18, 0
	ds_read_b128 v[232:235], v199 offset:36864
	ds_read_b128 v[236:239], v199 offset:49152
	ds_read_b128 v[240:243], v205 offset:36864
	ds_read_b128 v[248:251], v205 offset:49152
	ds_read_b128 v[244:247], v206 offset:36864
	v_exp_f32_e32 v162, v162
	v_add_f32_e32 v211, v225, v228
	v_exp_f32_e32 v163, v163
	v_add_f32_e32 v211, v226, v211
	v_exp_f32_e32 v160, v160
	s_waitcnt lgkmcnt(3)
	v_mfma_f32_32x32x16_bf16 v[80:95], v[232:235], v[124:127], 0
	ds_read_b128 v[232:235], v206 offset:49152
	v_add_f32_e32 v211, v229, v211
	v_exp_f32_e32 v161, v161
	v_add_f32_e32 v211, v227, v211
	v_exp_f32_e32 v158, v158
	v_mfma_f32_32x32x16_bf16 v[64:79], v[236:239], v[124:127], 0
	ds_read_b128 v[236:239], v208 offset:36864
	v_add_f32_e32 v211, v230, v211
	v_exp_f32_e32 v159, v159
	v_add_f32_e32 v211, v223, v211
	v_exp_f32_e32 v156, v156
	s_waitcnt lgkmcnt(3)
	v_mfma_f32_32x32x16_bf16 v[80:95], v[240:243], v[120:123], v[80:95]
	ds_read_b128 v[240:243], v208 offset:49152
	v_add_f32_e32 v211, v224, v211
	v_exp_f32_e32 v157, v157
	v_add_f32_e32 v211, v219, v211
	v_exp_f32_e32 v154, v154
	v_mfma_f32_32x32x16_bf16 v[64:79], v[248:251], v[120:123], v[64:79]
	ds_read_b128 v[248:251], v207 offset:36864
	v_add_f32_e32 v211, v221, v211
	v_exp_f32_e32 v155, v155
	v_add_f32_e32 v211, v220, v211
	v_exp_f32_e32 v152, v152
	s_waitcnt lgkmcnt(3)
	v_mfma_f32_32x32x16_bf16 v[80:95], v[244:247], v[116:119], v[80:95]
	ds_read_b128 v[244:247], v207 offset:49152
	v_add_f32_e32 v211, v222, v211
	v_exp_f32_e32 v153, v153
	v_add_f32_e32 v211, v215, v211
	v_exp_f32_e32 v150, v150
	v_mfma_f32_32x32x16_bf16 v[64:79], v[232:235], v[116:119], v[64:79]
	ds_read_b128 v[232:235], v204 offset:36864
	v_add_f32_e32 v211, v217, v211
	v_exp_f32_e32 v151, v151
	v_add_f32_e32 v211, v216, v211
	v_exp_f32_e32 v148, v148
	s_waitcnt lgkmcnt(3)
	v_mfma_f32_32x32x16_bf16 v[80:95], v[236:239], v[112:115], v[80:95]
	ds_read_b128 v[236:239], v204 offset:49152
	v_add_f32_e32 v211, v218, v211
	v_exp_f32_e32 v149, v149
	v_add_f32_e32 v212, v162, v163
	v_add_f32_e32 v212, v160, v212
	v_add_f32_e32 v212, v161, v212
	v_mfma_f32_32x32x16_bf16 v[64:79], v[240:243], v[112:115], v[64:79]
	ds_read_b128 v[240:243], v203 offset:36864
	v_add_f32_e32 v212, v158, v212
	v_add_f32_e32 v212, v159, v212
	v_add_f32_e32 v212, v156, v212
	v_add_f32_e32 v212, v157, v212
	v_add_f32_e32 v212, v154, v212
	v_add_f32_e32 v212, v155, v212
	s_waitcnt lgkmcnt(3)
	v_mfma_f32_32x32x16_bf16 v[80:95], v[248:251], v[108:111], v[80:95]
	ds_read_b128 v[248:251], v203 offset:49152
	v_add_f32_e32 v212, v152, v212
	v_add_f32_e32 v212, v153, v212
	v_add_f32_e32 v212, v150, v212
	v_add_f32_e32 v212, v151, v212
	v_add_f32_e32 v212, v148, v212
	v_add_f32_e32 v212, v149, v212
	v_mfma_f32_32x32x16_bf16 v[64:79], v[244:247], v[108:111], v[64:79]
	ds_read_b128 v[244:247], v200 offset:36864
	v_add_f32_e32 v211, v211, v212
	v_mov_b32_e32 v212, v211
	s_lshl_b32 s19, s18, 14
	v_add_u32_e32 v231, s19, v183
	s_waitcnt vmcnt(0)
	ds_write_b128 v231, v[140:143]
	v_add_u32_e32 v140, s19, v184
	ds_write_b128 v140, v[144:147]
	ds_write_b128 v185, v[136:139] offset:12288
	s_waitcnt lgkmcnt(6)
	v_mfma_f32_32x32x16_bf16 v[80:95], v[232:235], v[104:107], v[80:95]
	ds_read_b128 v[232:235], v200 offset:49152
	ds_write_b128 v185, v[132:135] offset:24576
	s_mov_b32 s18, 0xfffa0000
	ds_write_b128 v186, v[128:131] offset:12288
	v_add_co_u32_e32 v128, vcc, s18, v168
	s_mov_b32 s18, 0xfffc0000
	s_nop 0
	v_addc_co_u32_e32 v129, vcc, -1, v169, vcc
	v_add_co_u32_e32 v130, vcc, s18, v168
	s_movk_i32 s18, 0xe000
	s_nop 0
	v_addc_co_u32_e32 v131, vcc, -1, v169, vcc
	v_mfma_f32_32x32x16_bf16 v[64:79], v[236:239], v[104:107], v[64:79]
	ds_read_b128 v[236:239], v191 offset:36864
	global_load_dwordx4 v[140:143], v[128:129], off
	global_load_dwordx4 v[136:139], v[128:129], off offset:-256
	global_load_dwordx4 v[144:147], v[130:131], off
	global_load_dwordx4 v[132:135], v[130:131], off offset:-256
	v_add_co_u32_e32 v128, vcc, s18, v166
	s_nop 1
	v_addc_co_u32_e32 v129, vcc, -1, v167, vcc
	s_waitcnt lgkmcnt(8)
; __device__ __forceinline__ void finishSM(f32x16& p0, f32x16& p1, float alpha, float& l_reg, bf16x8& pa0, bf16x8& pa1, bf16x8& pa2, bf16x8& pa3) {
;     ...
;   PK4(p0, 0, pa0); PK4(p0, 8, pa1); PK4(p1, 0, pa2); PK4(p1, 8, pa3);
;     ...
; }
; __device__ __forceinline__ void qkt(f32x16& p0, f32x16& p1, const char* Ks, const bf16x8* qr, const char* qrl, int r32, int hi) {
;   p0 = f32x16{}; p1 = f32x16{};
; #pragma unroll
;   for (int d0 = 0; d0 < 8; ++d0) { int cb = (d0 * 16 + hi * 8) * 2;
;     bf16x8 b0 = *reinterpret_cast<const bf16x8*>(Ks + KSWZ(r32, cb));
;     bf16x8 b1 = *reinterpret_cast<const bf16x8*>(Ks + KSWZ(32 + r32, cb));
;     p0 = __builtin_amdgcn_mfma_f32_32x32x16_bf16(b0, qr[d0], p0, 0, 0, 0);
;     p1 = __builtin_amdgcn_mfma_f32_32x32x16_bf16(b1, qr[d0], p1, 0, 0, 0); }
; #pragma unroll
;   for (int d0 = 8; d0 < 12; ++d0) { int cb = (d0 * 16 + hi * 8) * 2;
;     bf16x8 b0 = *reinterpret_cast<const bf16x8*>(Ks + KSWZ(r32, cb));
;     bf16x8 b1 = *reinterpret_cast<const bf16x8*>(Ks + KSWZ(32 + r32, cb));
;     bf16x8 qf = *reinterpret_cast<const bf16x8*>(qrl + (((2 * (d0 - 8) + hi) ^ ((r32 >> 1) & 7)) << 4));
;     p0 = __builtin_amdgcn_mfma_f32_32x32x16_bf16(b0, qf, p0, 0, 0, 0);
;     p1 = __builtin_amdgcn_mfma_f32_32x32x16_bf16(b1, qf, p1, 0, 0, 0); }
; }
; __device__ __forceinline__ int v_st(int k, int c) { const int kk = (k & ~0xC) | ((k & 4) << 1) | ((k & 8) >> 1); return ((kk >> 3) * 4 + (c >> 5)) * 512 + ((kk & 7) * 32 + (c & 31)) * 2; }
; __device__ __forceinline__ int v_rd_base(int lane) { return ((lane & 3) << 3) | (((lane >> 2) & 3) << 6) | (((lane >> 4) & 1) << 5) | (((lane >> 5) & 1) << 8); }
; template <int OFF> __device__ __forceinline__ s16x4 tr_read(int vb) {
;   s16x4 r; asm volatile("ds_read_b64_tr_b16 %0, %1 offset:%2" : "=&v"(r) : "v"(vb), "i"(OFF) : "memory"); return r;
; }
; template <int D0> __device__ __forceinline__ void pv_one(f32x16& od, int vb, bf16x8 pa0, bf16x8 pa1, bf16x8 pa2, bf16x8 pa3) {
;   const s16x4 l0 = tr_read<v_rd_off(D0, 0, 0)>(vb), h0 = tr_read<v_rd_off(D0, 0, 1)>(vb), l1 = tr_read<v_rd_off(D0, 1, 0)>(vb), h1 = tr_read<v_rd_off(D0, 1, 1)>(vb);
;   const s16x4 l2 = tr_read<v_rd_off(D0, 2, 0)>(vb), h2 = tr_read<v_rd_off(D0, 2, 1)>(vb), l3 = tr_read<v_rd_off(D0, 3, 0)>(vb), h3 = tr_read<v_rd_off(D0, 3, 1)>(vb);
;   asm volatile("s_waitcnt lgkmcnt(0)" ::: "memory"); SBAR();
	v_mfma_f32_32x32x16_bf16 v[80:95], v[240:243], v[100:103], v[80:95]
	ds_read_b128 v[240:243], v202 offset:49152
	global_load_dwordx4 v[128:131], v[128:129], off
	v_cvt_pk_bf16_f32 v158, v158, v159
	v_cvt_pk_bf16_f32 v159, v156, v157
	v_permlane32_swap_b32_e32 v211, v212
	v_cvt_pk_bf16_f32 v156, v162, v163
	v_cvt_pk_bf16_f32 v157, v160, v161
	v_mfma_f32_32x32x16_bf16 v[64:79], v[248:251], v[100:103], v[64:79]
	ds_read_b128 v[248:251], v182
	v_cvt_pk_bf16_f32 v160, v154, v155
	v_cvt_pk_bf16_f32 v161, v152, v153
	v_cvt_pk_bf16_f32 v162, v150, v151
	v_cvt_pk_bf16_f32 v163, v148, v149
	v_add_f32_e32 v211, v211, v212
	v_cvt_pk_bf16_f32 v148, v225, v228
	s_waitcnt lgkmcnt(5)
	v_mfma_f32_32x32x16_bf16 v[80:95], v[244:247], v[96:99], v[80:95]
	ds_read_b128 v[244:247], v198 offset:36864
	v_cvt_pk_bf16_f32 v149, v226, v229
	v_cvt_pk_bf16_f32 v150, v227, v230
	v_cvt_pk_bf16_f32 v151, v223, v224
	v_cvt_pk_bf16_f32 v152, v219, v221
	v_cvt_pk_bf16_f32 v153, v220, v222
	v_cvt_pk_bf16_f32 v154, v215, v217
	v_mfma_f32_32x32x16_bf16 v[64:79], v[232:235], v[96:99], v[64:79]
	ds_read_b128 v[232:235], v201 offset:49152
	v_cvt_pk_bf16_f32 v155, v216, v218
	v_fma_f32 v176, v209, v176, v211
	s_waitcnt lgkmcnt(2)
	v_mfma_f32_32x32x16_bf16 v[80:95], v[236:239], v[248:251], v[80:95]
	ds_read_b128 v[236:239], v181
	v_mfma_f32_32x32x16_bf16 v[64:79], v[240:243], v[248:251], v[64:79]
	ds_read_b128 v[240:243], v187 offset:36864
	ds_read_b128 v[248:251], v189 offset:49152
	s_waitcnt lgkmcnt(2)
	v_mfma_f32_32x32x16_bf16 v[80:95], v[244:247], v[236:239], v[80:95]
	ds_read_b128 v[244:247], v179
	v_mfma_f32_32x32x16_bf16 v[64:79], v[232:235], v[236:239], v[64:79]
	ds_read_b128 v[232:235], v188 offset:36864
	ds_read_b128 v[236:239], v190 offset:49152
	s_waitcnt lgkmcnt(2)
	v_mfma_f32_32x32x16_bf16 v[80:95], v[240:243], v[244:247], v[80:95]
	ds_read_b128 v[240:243], v177
	v_mfma_f32_32x32x16_bf16 v[64:79], v[248:251], v[244:247], v[64:79]
	s_waitcnt lgkmcnt(0)
	v_mfma_f32_32x32x16_bf16 v[80:95], v[232:235], v[240:243], v[80:95]
	v_mfma_f32_32x32x16_bf16 v[64:79], v[236:239], v[240:243], v[64:79]
	s_lshl_b32 s31, s30, 14
	v_add_u32_e32 v180, s31, v178
	ds_read_b64_tr_b16 v[232:233], v180 offset:0
	ds_read_b64_tr_b16 v[234:235], v180 offset:2048
	ds_read_b64_tr_b16 v[236:237], v180 offset:512
	ds_read_b64_tr_b16 v[238:239], v180 offset:2560
	ds_read_b64_tr_b16 v[240:241], v180 offset:1024
	ds_read_b64_tr_b16 v[242:243], v180 offset:3072
	ds_read_b64_tr_b16 v[248:249], v180 offset:1536
	ds_read_b64_tr_b16 v[250:251], v180 offset:3584
	ds_read_b64_tr_b16 v[244:245], v180 offset:4096
	ds_read_b64_tr_b16 v[246:247], v180 offset:6144
	s_nop 3
	v_max3_f32 v194, v80, v81, v82
	v_max3_f32 v195, v64, v65, v66
	v_max3_f32 v194, v194, v83, v84
	v_max3_f32 v195, v195, v67, v68
	s_waitcnt lgkmcnt(6)
	v_mfma_f32_32x32x16_bf16 v[32:47], v[148:151], v[232:235], v[32:47]
	ds_read_b64_tr_b16 v[232:233], v180 offset:4608
	ds_read_b64_tr_b16 v[234:235], v180 offset:6656
	v_max3_f32 v194, v194, v85, v86
	v_max3_f32 v195, v195, v69, v70
	v_max3_f32 v194, v194, v87, v88
	v_max3_f32 v195, v195, v71, v72
	v_mfma_f32_32x32x16_bf16 v[48:63], v[148:151], v[236:239], v[48:63]
	ds_read_b64_tr_b16 v[236:237], v180 offset:5120
	ds_read_b64_tr_b16 v[238:239], v180 offset:7168
	v_max3_f32 v194, v194, v89, v90
	v_max3_f32 v195, v195, v73, v74
	v_max3_f32 v194, v194, v91, v92
	v_max3_f32 v195, v195, v75, v76
	s_waitcnt lgkmcnt(6)
	v_mfma_f32_32x32x16_bf16 v[16:31], v[148:151], v[240:243], v[16:31]
	ds_read_b64_tr_b16 v[240:241], v180 offset:5632
	ds_read_b64_tr_b16 v[242:243], v180 offset:7680
	v_max3_f32 v194, v194, v93, v94
	v_max3_f32 v195, v195, v77, v78
	v_max3_f32 v194, v194, v95, v195
	v_max_f32_e32 v194, v194, v79
	v_mfma_f32_32x32x16_bf16 v[0:15], v[148:151], v[248:251], v[0:15]
	ds_read_b64_tr_b16 v[248:249], v180 offset:8192
	ds_read_b64_tr_b16 v[250:251], v180 offset:10240
	v_mov_b32_e32 v195, v194
	s_nop 1
	v_permlane32_swap_b32_e32 v194, v195
	v_max_f32_e32 v194, v194, v195
	s_waitcnt lgkmcnt(6)
	v_mfma_f32_32x32x16_bf16 v[32:47], v[152:155], v[244:247], v[32:47]
	ds_read_b64_tr_b16 v[244:245], v180 offset:8704
	ds_read_b64_tr_b16 v[246:247], v180 offset:10752
	v_sub_f32_e32 v195, v194, v210
	v_cmp_ge_f32_e32 vcc, s15, v195
	v_mfma_f32_32x32x16_bf16 v[48:63], v[152:155], v[232:235], v[48:63]
	ds_read_b64_tr_b16 v[232:233], v180 offset:9216
	ds_read_b64_tr_b16 v[234:235], v180 offset:11264
	s_cmp_eq_u64 vcc, exec
	s_cselect_b64 s[40:41], -1, 0
	s_cbranch_scc1 .Lattn_fast1p
	v_max_f32_e32 v194, v210, v194
	v_sub_f32_e32 v195, v210, v194
	v_mul_f32_e32 v195, 0x3dd53b94, v195
	v_exp_f32_e32 v214, v195
	v_mov_b32_e32 v210, v194
	s_branch .Lattn_join1p

; __device__ __forceinline__ void partialSM(f32x16& p0, f32x16& p1, float& m_reg, float& mn, float& alpha) {
;     ...
;   float mnC = -mn * C;
; #pragma unroll
;   for (int r = 0; r < 16; ++r) p0[r] = fmaf(p0[r], C, mnC);
; #pragma unroll
;   for (int r = 0; r < 16; ++r) p1[r] = fmaf(p1[r], C, mnC);
; template <int D0> __device__ __forceinline__ void pv_one(f32x16& od, int vb, bf16x8 pa0, bf16x8 pa1, bf16x8 pa2, bf16x8 pa3) {
;   const s16x4 l0 = tr_read<v_rd_off(D0, 0, 0)>(vb), h0 = tr_read<v_rd_off(D0, 0, 1)>(vb), l1 = tr_read<v_rd_off(D0, 1, 0)>(vb), h1 = tr_read<v_rd_off(D0, 1, 1)>(vb);
;   const s16x4 l2 = tr_read<v_rd_off(D0, 2, 0)>(vb), h2 = tr_read<v_rd_off(D0, 2, 1)>(vb), l3 = tr_read<v_rd_off(D0, 3, 0)>(vb), h3 = tr_read<v_rd_off(D0, 3, 1)>(vb);
;   asm volatile("s_waitcnt lgkmcnt(0)" ::: "memory"); SBAR();
;     ...
;   od = __builtin_amdgcn_mfma_f32_32x32x16_bf16(pa0, PK(l0, h0), od, 0, 0, 0);
;   od = __builtin_amdgcn_mfma_f32_32x32x16_bf16(pa1, PK(l1, h1), od, 0, 0, 0);
;   od = __builtin_amdgcn_mfma_f32_32x32x16_bf16(pa2, PK(l2, h2), od, 0, 0, 0);
;   od = __builtin_amdgcn_mfma_f32_32x32x16_bf16(pa3, PK(l3, h3), od, 0, 0, 0);
;     ...
; }
; __device__ __forceinline__ void pv_d0(f32x16* o, int vb, bf16x8 pa0, bf16x8 pa1, bf16x8 pa2, bf16x8 pa3) {
;   pv_one<0>(o[0], vb, pa0, pa1, pa2, pa3); pv_one<1>(o[1], vb, pa0, pa1, pa2, pa3); pv_one<2>(o[2], vb, pa0, pa1, pa2, pa3); pv_one<3>(o[3], vb, pa0, pa1, pa2, pa3);
; }
; __device__ __forceinline__ void attn_unit(const bf16_t* __restrict__ Qb, const bf16_t* __restrict__ Kn, const bf16_t* __restrict__ Vh, const bf16_t* __restrict__ Kr,
;                                           bf16_t* GO, int seq, char* lds, const int tid) {
;   const int wid = tid >> 6, lane = tid & 63, r32 = lane & 31, hi = lane >> 5;
;   char* V_lds = lds; char* K_lds = lds + 3 * SHM_V;
;   float* ws = (float*)(lds + 3 * SHM_V + 3 * SHM_K) + wid * 64; float* li_l = ws; float* al_l = ws + 32;
;   if (wid < 4) __builtin_amdgcn_s_setprio(2); else __builtin_amdgcn_s_setprio(0);
;   float m_reg = -1e30f, l_reg = 0; f32x16 o[4] = {}; bf16x8 qr[8];
;   char* qrl = lds + 3 * SHM_V + 3 * SHM_K + NW * 64 * 4 + wid * 4096 + r32 * 128;
;   const bf16_t* Qw = Qb + (long)(wid * QBLK + r32) * LDQ + hi * 8;
; #pragma unroll
;   for (int d0 = 0; d0 < 8; ++d0) qr[d0] = *reinterpret_cast<const bf16x8*>(Qw + d0 * 16);
; #pragma unroll
.Lattn_join1p:
	v_mul_f32_e32 v194, 0xbdd53b94, v210
	s_waitcnt lgkmcnt(6)
	v_mfma_f32_32x32x16_bf16 v[16:31], v[152:155], v[236:239], v[16:31]
	ds_read_b64_tr_b16 v[236:237], v180 offset:9728
	ds_read_b64_tr_b16 v[238:239], v180 offset:11776
	v_fmamk_f32 v225, v80, 0x3dd53b94, v194
	v_fmamk_f32 v228, v81, 0x3dd53b94, v194
	v_fmamk_f32 v226, v82, 0x3dd53b94, v194
	v_fmamk_f32 v229, v83, 0x3dd53b94, v194
	v_mfma_f32_32x32x16_bf16 v[0:15], v[152:155], v[240:243], v[0:15]
	ds_read_b64_tr_b16 v[240:241], v180 offset:12288
	ds_read_b64_tr_b16 v[242:243], v180 offset:14336
	v_fmamk_f32 v150, v76, 0x3dd53b94, v194
	v_fmamk_f32 v151, v77, 0x3dd53b94, v194
	v_fmamk_f32 v148, v78, 0x3dd53b94, v194
	v_fmamk_f32 v149, v79, 0x3dd53b94, v194
	s_waitcnt lgkmcnt(6)
	v_mfma_f32_32x32x16_bf16 v[32:47], v[156:159], v[248:251], v[32:47]
	ds_read_b64_tr_b16 v[248:249], v180 offset:12800
	ds_read_b64_tr_b16 v[250:251], v180 offset:14848
	v_fmamk_f32 v227, v84, 0x3dd53b94, v194
	v_fmamk_f32 v230, v85, 0x3dd53b94, v194
	v_fmamk_f32 v223, v86, 0x3dd53b94, v194
	v_fmamk_f32 v224, v87, 0x3dd53b94, v194
	v_mfma_f32_32x32x16_bf16 v[48:63], v[156:159], v[244:247], v[48:63]
	ds_read_b64_tr_b16 v[244:245], v180 offset:13312
	ds_read_b64_tr_b16 v[246:247], v180 offset:15360
	v_fmamk_f32 v154, v72, 0x3dd53b94, v194
	v_fmamk_f32 v155, v73, 0x3dd53b94, v194
	v_fmamk_f32 v152, v74, 0x3dd53b94, v194
	v_fmamk_f32 v153, v75, 0x3dd53b94, v194
	s_waitcnt lgkmcnt(6)
	v_mfma_f32_32x32x16_bf16 v[16:31], v[156:159], v[232:235], v[16:31]
	ds_read_b64_tr_b16 v[232:233], v180 offset:13824
	ds_read_b64_tr_b16 v[234:235], v180 offset:15872
	v_fmamk_f32 v219, v88, 0x3dd53b94, v194
	v_fmamk_f32 v221, v89, 0x3dd53b94, v194
	v_fmamk_f32 v220, v90, 0x3dd53b94, v194
	v_fmamk_f32 v222, v91, 0x3dd53b94, v194
	v_mfma_f32_32x32x16_bf16 v[0:15], v[156:159], v[236:239], v[0:15]
	v_fmamk_f32 v158, v68, 0x3dd53b94, v194
	v_fmamk_f32 v159, v69, 0x3dd53b94, v194
	v_fmamk_f32 v156, v70, 0x3dd53b94, v194
	v_fmamk_f32 v157, v71, 0x3dd53b94, v194
	s_waitcnt lgkmcnt(0)
	s_barrier
	ds_read_b128 v[236:239], v199 offset:12288
	v_mfma_f32_32x32x16_bf16 v[32:47], v[160:163], v[240:243], v[32:47]
	ds_read_b128 v[240:243], v199 offset:24576
	v_fmamk_f32 v215, v92, 0x3dd53b94, v194
	v_fmamk_f32 v217, v93, 0x3dd53b94, v194
	v_fmamk_f32 v216, v94, 0x3dd53b94, v194
	v_fmamk_f32 v218, v95, 0x3dd53b94, v194
	v_mfma_f32_32x32x16_bf16 v[48:63], v[160:163], v[248:251], v[48:63]
	ds_read_b128 v[248:251], v205 offset:12288
	v_mfma_f32_32x32x16_bf16 v[16:31], v[160:163], v[244:247], v[16:31]
	ds_read_b128 v[244:247], v205 offset:24576
	v_mfma_f32_32x32x16_bf16 v[0:15], v[160:163], v[232:235], v[0:15]
	ds_read_b128 v[232:235], v206 offset:12288
	v_fmamk_f32 v162, v64, 0x3dd53b94, v194
	v_fmamk_f32 v163, v65, 0x3dd53b94, v194
	v_fmamk_f32 v160, v66, 0x3dd53b94, v194
	v_fmamk_f32 v161, v67, 0x3dd53b94, v194
	s_and_b64 vcc, exec, s[40:41]
	s_cbranch_vccnz .Lattn_skip_rs1p
	s_and_saveexec_b64 s[18:19], s[38:39]
	ds_write_b32 v175, v214 offset:128
	s_or_b64 exec, exec, s[18:19]
	s_waitcnt lgkmcnt(0)
	v_add_u32_e32 v194, v173, v164
	ds_read_b128 v[64:67], v194 offset:224
	ds_read_b128 v[68:71], v194 offset:192
	ds_read_b128 v[72:75], v194 offset:160
	ds_read_b128 v[76:79], v194 offset:128
	s_waitcnt lgkmcnt(0)
	v_pk_mul_f32 v[44:45], v[44:45], v[64:65]
	v_pk_mul_f32 v[46:47], v[46:47], v[66:67]
	v_pk_mul_f32 v[40:41], v[40:41], v[68:69]
	v_pk_mul_f32 v[42:43], v[42:43], v[70:71]
	v_pk_mul_f32 v[36:37], v[36:37], v[72:73]
	v_pk_mul_f32 v[38:39], v[38:39], v[74:75]
	v_pk_mul_f32 v[32:33], v[32:33], v[76:77]
	v_pk_mul_f32 v[34:35], v[34:35], v[78:79]
	v_pk_mul_f32 v[60:61], v[60:61], v[64:65]
	v_pk_mul_f32 v[62:63], v[62:63], v[66:67]
	v_pk_mul_f32 v[56:57], v[56:57], v[68:69]
	v_pk_mul_f32 v[58:59], v[58:59], v[70:71]
	v_pk_mul_f32 v[52:53], v[52:53], v[72:73]
	v_pk_mul_f32 v[54:55], v[54:55], v[74:75]
	v_pk_mul_f32 v[48:49], v[48:49], v[76:77]
	v_pk_mul_f32 v[50:51], v[50:51], v[78:79]
	v_pk_mul_f32 v[28:29], v[28:29], v[64:65]
	v_pk_mul_f32 v[30:31], v[30:31], v[66:67]
	v_pk_mul_f32 v[24:25], v[24:25], v[68:69]
	v_pk_mul_f32 v[26:27], v[26:27], v[70:71]
	v_pk_mul_f32 v[20:21], v[20:21], v[72:73]
	v_pk_mul_f32 v[22:23], v[22:23], v[74:75]
	v_pk_mul_f32 v[16:17], v[16:17], v[76:77]
	v_pk_mul_f32 v[18:19], v[18:19], v[78:79]
	v_pk_mul_f32 v[12:13], v[12:13], v[64:65]
	v_pk_mul_f32 v[14:15], v[14:15], v[66:67]
	v_pk_mul_f32 v[8:9], v[8:9], v[68:69]
	v_pk_mul_f32 v[10:11], v[10:11], v[70:71]
	v_pk_mul_f32 v[4:5], v[4:5], v[72:73]
	v_pk_mul_f32 v[6:7], v[6:7], v[74:75]
	v_pk_mul_f32 v[0:1], v[0:1], v[76:77]
	v_pk_mul_f32 v[2:3], v[2:3], v[78:79]
; __device__ __forceinline__ void partialSM(f32x16& p0, f32x16& p1, float& m_reg, float& mn, float& alpha) {
;     ...
;   for (int r = 0; r < 16; ++r) p0[r] = __builtin_amdgcn_exp2f(p0[r]);
; }
; __device__ __forceinline__ void finishSM(f32x16& p0, f32x16& p1, float alpha, float& l_reg, bf16x8& pa0, bf16x8& pa1, bf16x8& pa2, bf16x8& pa3) {
; #pragma unroll
;   for (int r = 0; r < 16; ++r) p1[r] = __builtin_amdgcn_exp2f(p1[r]);
;   float ps = 0;
; #pragma unroll
;   for (int r = 0; r < 16; ++r) ps += p0[r];
; #pragma unroll
;   for (int r = 0; r < 16; ++r) ps += p1[r];
;   { auto rr = __builtin_amdgcn_permlane32_swap(__float_as_uint(ps), __float_as_uint(ps), false, false);
;     ps = __uint_as_float(rr[0]) + __uint_as_float(rr[1]); }
;   l_reg = l_reg * alpha + ps;
;     ...
;   PK4(p0, 0, pa0); PK4(p0, 8, pa1); PK4(p1, 0, pa2); PK4(p1, 8, pa3);
;     ...
; }
; __device__ __forceinline__ void qkt(f32x16& p0, f32x16& p1, const char* Ks, const bf16x8* qr, const char* qrl, int r32, int hi) {
;   p0 = f32x16{}; p1 = f32x16{};
; #pragma unroll
;   for (int d0 = 0; d0 < 8; ++d0) { int cb = (d0 * 16 + hi * 8) * 2;
;     bf16x8 b0 = *reinterpret_cast<const bf16x8*>(Ks + KSWZ(r32, cb));
;     bf16x8 b1 = *reinterpret_cast<const bf16x8*>(Ks + KSWZ(32 + r32, cb));
;     p0 = __builtin_amdgcn_mfma_f32_32x32x16_bf16(b0, qr[d0], p0, 0, 0, 0);
;     p1 = __builtin_amdgcn_mfma_f32_32x32x16_bf16(b1, qr[d0], p1, 0, 0, 0); }
; #pragma unroll
;   for (int d0 = 8; d0 < 12; ++d0) { int cb = (d0 * 16 + hi * 8) * 2;
;     bf16x8 b0 = *reinterpret_cast<const bf16x8*>(Ks + KSWZ(r32, cb));
;     bf16x8 b1 = *reinterpret_cast<const bf16x8*>(Ks + KSWZ(32 + r32, cb));
;     bf16x8 qf = *reinterpret_cast<const bf16x8*>(qrl + (((2 * (d0 - 8) + hi) ^ ((r32 >> 1) & 7)) << 4));
;     p0 = __builtin_amdgcn_mfma_f32_32x32x16_bf16(b0, qf, p0, 0, 0, 0);
;     p1 = __builtin_amdgcn_mfma_f32_32x32x16_bf16(b1, qf, p1, 0, 0, 0); }
; }
; __device__ __forceinline__ void attn_unit(const bf16_t* __restrict__ Qb, const bf16_t* __restrict__ Kn, const bf16_t* __restrict__ Vh, const bf16_t* __restrict__ Kr,
;                                           bf16_t* GO, int seq, char* lds, const int tid) {
;     ...
;   f32x16 pA0, pA1, pB0, pB1; float mnA, mnB, alA, alB; bf16x8 pa0, pa1, pa2, pa3; const int NT = seq / KVBLK;
;     ...
;   SLOAD(0, 0); SWRITE(0, 0); SLOAD(0, KVBLK); LBAR();
.Lattn_skip_rs1p:
	v_exp_f32_e32 v225, v225
	v_exp_f32_e32 v228, v228
	v_exp_f32_e32 v226, v226
	v_add_f32_e32 v211, v225, v228
	s_waitcnt lgkmcnt(3)
	v_mfma_f32_32x32x16_bf16 v[80:95], v[236:239], v[124:127], 0
	ds_read_b128 v[236:239], v206 offset:24576
	v_exp_f32_e32 v229, v229
	v_add_f32_e32 v211, v226, v211
	v_exp_f32_e32 v227, v227
	v_add_f32_e32 v211, v229, v211
	v_mfma_f32_32x32x16_bf16 v[64:79], v[240:243], v[124:127], 0
	ds_read_b128 v[240:243], v208 offset:12288
	v_exp_f32_e32 v230, v230
	v_add_f32_e32 v211, v227, v211
	v_exp_f32_e32 v223, v223
	v_add_f32_e32 v211, v230, v211
	s_waitcnt lgkmcnt(3)
	v_mfma_f32_32x32x16_bf16 v[80:95], v[248:251], v[120:123], v[80:95]
	ds_read_b128 v[248:251], v208 offset:24576
	v_exp_f32_e32 v224, v224
	v_add_f32_e32 v211, v223, v211
	v_exp_f32_e32 v219, v219
	v_add_f32_e32 v211, v224, v211
	v_mfma_f32_32x32x16_bf16 v[64:79], v[244:247], v[120:123], v[64:79]
	ds_read_b128 v[244:247], v207 offset:12288
	v_exp_f32_e32 v221, v221
	v_add_f32_e32 v211, v219, v211
	v_exp_f32_e32 v220, v220
	v_add_f32_e32 v211, v221, v211
	s_waitcnt lgkmcnt(3)
	v_mfma_f32_32x32x16_bf16 v[80:95], v[232:235], v[116:119], v[80:95]
	ds_read_b128 v[232:235], v207 offset:24576
	v_exp_f32_e32 v222, v222
	v_add_f32_e32 v211, v220, v211
	v_exp_f32_e32 v215, v215
	v_add_f32_e32 v211, v222, v211
	v_mfma_f32_32x32x16_bf16 v[64:79], v[236:239], v[116:119], v[64:79]
	ds_read_b128 v[236:239], v204 offset:12288
	v_exp_f32_e32 v217, v217
	v_add_f32_e32 v211, v215, v211
	v_exp_f32_e32 v216, v216
	v_add_f32_e32 v211, v217, v211
	s_waitcnt lgkmcnt(3)
	v_mfma_f32_32x32x16_bf16 v[80:95], v[240:243], v[112:115], v[80:95]
	ds_read_b128 v[240:243], v204 offset:24576
	v_exp_f32_e32 v218, v218
	v_add_f32_e32 v211, v216, v211
	v_exp_f32_e32 v162, v162
	v_add_f32_e32 v211, v218, v211
	v_mfma_f32_32x32x16_bf16 v[64:79], v[248:251], v[112:115], v[64:79]
	ds_read_b128 v[248:251], v203 offset:12288
	v_exp_f32_e32 v163, v163
	v_exp_f32_e32 v160, v160
	v_exp_f32_e32 v161, v161
	s_waitcnt lgkmcnt(3)
	v_mfma_f32_32x32x16_bf16 v[80:95], v[244:247], v[108:111], v[80:95]
	ds_read_b128 v[244:247], v203 offset:24576
	v_exp_f32_e32 v158, v158
	v_exp_f32_e32 v159, v159
	v_exp_f32_e32 v156, v156
	v_mfma_f32_32x32x16_bf16 v[64:79], v[232:235], v[108:111], v[64:79]
	ds_read_b128 v[232:235], v200 offset:12288
	v_exp_f32_e32 v157, v157
	v_exp_f32_e32 v154, v154
	v_exp_f32_e32 v155, v155
	s_waitcnt lgkmcnt(3)
	v_mfma_f32_32x32x16_bf16 v[80:95], v[236:239], v[104:107], v[80:95]
	ds_read_b128 v[236:239], v200 offset:24576
	v_exp_f32_e32 v152, v152
	v_exp_f32_e32 v153, v153
	v_exp_f32_e32 v150, v150
	v_mfma_f32_32x32x16_bf16 v[64:79], v[240:243], v[104:107], v[64:79]
	ds_read_b128 v[240:243], v191 offset:12288
	v_exp_f32_e32 v151, v151
	v_exp_f32_e32 v148, v148
	v_exp_f32_e32 v149, v149
	s_waitcnt lgkmcnt(3)
	v_mfma_f32_32x32x16_bf16 v[80:95], v[248:251], v[100:103], v[80:95]
	ds_read_b128 v[248:251], v202 offset:24576
	v_add_f32_e32 v212, v162, v163
	v_add_f32_e32 v212, v160, v212
	v_add_f32_e32 v212, v161, v212
	v_add_f32_e32 v212, v158, v212
	v_add_f32_e32 v212, v159, v212
	v_add_f32_e32 v212, v156, v212
	v_mfma_f32_32x32x16_bf16 v[64:79], v[244:247], v[100:103], v[64:79]
	ds_read_b128 v[244:247], v182
	v_add_f32_e32 v212, v157, v212
	v_add_f32_e32 v212, v154, v212
	v_add_f32_e32 v212, v155, v212
	v_add_f32_e32 v212, v152, v212
	v_add_f32_e32 v212, v153, v212
	v_add_f32_e32 v212, v150, v212
	s_waitcnt lgkmcnt(3)
	v_mfma_f32_32x32x16_bf16 v[80:95], v[232:235], v[96:99], v[80:95]
	ds_read_b128 v[232:235], v198 offset:12288
	v_add_f32_e32 v212, v151, v212
	v_add_f32_e32 v212, v148, v212
	v_add_f32_e32 v212, v149, v212
	v_add_f32_e32 v211, v211, v212
	v_mov_b32_e32 v212, v211
	v_add_u32_e32 v194, s31, v183
	s_waitcnt vmcnt(4)
	v_mfma_f32_32x32x16_bf16 v[64:79], v[236:239], v[96:99], v[64:79]
	ds_read_b128 v[236:239], v201 offset:24576
	ds_write_b128 v194, v[140:143]
	v_add_u32_e32 v194, s31, v184
	s_add_i32 s73, s73, 2
	s_cmp_ge_u32 s73, s45
	s_waitcnt vmcnt(2)
	ds_write_b128 v194, v[144:147]
	s_cselect_b64 s[28:29], -1, 0
	ds_write_b128 v185, v[136:139] offset:36864
	s_waitcnt vmcnt(1)
	ds_write_b128 v185, v[132:135] offset:49152
	s_and_b64 vcc, exec, s[28:29]
	s_waitcnt lgkmcnt(6)
	v_mfma_f32_32x32x16_bf16 v[80:95], v[240:243], v[244:247], v[80:95]
	ds_read_b128 v[240:243], v181
	s_waitcnt vmcnt(0)
	ds_write_b128 v186, v[128:131] offset:36864
	v_mfma_f32_32x32x16_bf16 v[64:79], v[248:251], v[244:247], v[64:79]
	ds_read_b128 v[248:251], v187 offset:12288
	ds_read_b128 v[244:247], v189 offset:24576
	s_cbranch_vccnz .Lattn_noloadp
	v_add_co_u32_e32 v128, vcc, 0xfffe0000, v168
	s_nop 1
	v_addc_co_u32_e32 v129, vcc, -1, v169, vcc
	global_load_dwordx4 v[140:143], v[128:129], off
	global_load_dwordx4 v[136:139], v[128:129], off offset:-256
	global_load_dwordx4 v[144:147], v[168:169], off
	global_load_dwordx4 v[132:135], v[168:169], off offset:-256
	s_nop 0
	global_load_dwordx4 v[128:131], v[166:167], off
; __device__ __forceinline__ void finishSM(f32x16& p0, f32x16& p1, float alpha, float& l_reg, bf16x8& pa0, bf16x8& pa1, bf16x8& pa2, bf16x8& pa3) {
;     ...
;   PK4(p0, 0, pa0); PK4(p0, 8, pa1); PK4(p1, 0, pa2); PK4(p1, 8, pa3);
;     ...
; }
; __device__ __forceinline__ void qkt(f32x16& p0, f32x16& p1, const char* Ks, const bf16x8* qr, const char* qrl, int r32, int hi) {
;   p0 = f32x16{}; p1 = f32x16{};
; #pragma unroll
;   for (int d0 = 0; d0 < 8; ++d0) { int cb = (d0 * 16 + hi * 8) * 2;
;     bf16x8 b0 = *reinterpret_cast<const bf16x8*>(Ks + KSWZ(r32, cb));
;     bf16x8 b1 = *reinterpret_cast<const bf16x8*>(Ks + KSWZ(32 + r32, cb));
;     p0 = __builtin_amdgcn_mfma_f32_32x32x16_bf16(b0, qr[d0], p0, 0, 0, 0);
;     p1 = __builtin_amdgcn_mfma_f32_32x32x16_bf16(b1, qr[d0], p1, 0, 0, 0); }
; #pragma unroll
;   for (int d0 = 8; d0 < 12; ++d0) { int cb = (d0 * 16 + hi * 8) * 2;
;     bf16x8 b0 = *reinterpret_cast<const bf16x8*>(Ks + KSWZ(r32, cb));
;     bf16x8 b1 = *reinterpret_cast<const bf16x8*>(Ks + KSWZ(32 + r32, cb));
;     bf16x8 qf = *reinterpret_cast<const bf16x8*>(qrl + (((2 * (d0 - 8) + hi) ^ ((r32 >> 1) & 7)) << 4));
;     p0 = __builtin_amdgcn_mfma_f32_32x32x16_bf16(b0, qf, p0, 0, 0, 0);
;     p1 = __builtin_amdgcn_mfma_f32_32x32x16_bf16(b1, qf, p1, 0, 0, 0); }
; }
; __device__ __forceinline__ int v_st(int k, int c) { const int kk = (k & ~0xC) | ((k & 4) << 1) | ((k & 8) >> 1); return ((kk >> 3) * 4 + (c >> 5)) * 512 + ((kk & 7) * 32 + (c & 31)) * 2; }
; __device__ __forceinline__ int v_rd_base(int lane) { return ((lane & 3) << 3) | (((lane >> 2) & 3) << 6) | (((lane >> 4) & 1) << 5) | (((lane >> 5) & 1) << 8); }
; template <int OFF> __device__ __forceinline__ s16x4 tr_read(int vb) {
;   s16x4 r; asm volatile("ds_read_b64_tr_b16 %0, %1 offset:%2" : "=&v"(r) : "v"(vb), "i"(OFF) : "memory"); return r;
; }
; template <int D0> __device__ __forceinline__ void pv_one(f32x16& od, int vb, bf16x8 pa0, bf16x8 pa1, bf16x8 pa2, bf16x8 pa3) {
;   const s16x4 l0 = tr_read<v_rd_off(D0, 0, 0)>(vb), h0 = tr_read<v_rd_off(D0, 0, 1)>(vb), l1 = tr_read<v_rd_off(D0, 1, 0)>(vb), h1 = tr_read<v_rd_off(D0, 1, 1)>(vb);
;   const s16x4 l2 = tr_read<v_rd_off(D0, 2, 0)>(vb), h2 = tr_read<v_rd_off(D0, 2, 1)>(vb), l3 = tr_read<v_rd_off(D0, 3, 0)>(vb), h3 = tr_read<v_rd_off(D0, 3, 1)>(vb);
;   asm volatile("s_waitcnt lgkmcnt(0)" ::: "memory"); SBAR();
.Lattn_noloadp:
	s_waitcnt lgkmcnt(3)
	v_mfma_f32_32x32x16_bf16 v[80:95], v[232:235], v[240:243], v[80:95]
	ds_read_b128 v[232:235], v179
	v_cvt_pk_bf16_f32 v158, v158, v159
	v_cvt_pk_bf16_f32 v159, v156, v157
	v_permlane32_swap_b32_e32 v211, v212
	v_cvt_pk_bf16_f32 v156, v162, v163
	v_cvt_pk_bf16_f32 v157, v160, v161
	v_cvt_pk_bf16_f32 v160, v154, v155
	v_mfma_f32_32x32x16_bf16 v[64:79], v[236:239], v[240:243], v[64:79]
	ds_read_b128 v[236:239], v188 offset:12288
	ds_read_b128 v[240:243], v190 offset:24576
	v_cvt_pk_bf16_f32 v161, v152, v153
	v_cvt_pk_bf16_f32 v162, v150, v151
	v_cvt_pk_bf16_f32 v163, v148, v149
	v_add_f32_e32 v211, v211, v212
	v_cvt_pk_bf16_f32 v148, v225, v228
	v_cvt_pk_bf16_f32 v149, v226, v229
	s_waitcnt lgkmcnt(2)
	v_mfma_f32_32x32x16_bf16 v[80:95], v[248:251], v[232:235], v[80:95]
	ds_read_b128 v[248:251], v177
	v_cvt_pk_bf16_f32 v150, v227, v230
	v_cvt_pk_bf16_f32 v151, v223, v224
	v_cvt_pk_bf16_f32 v152, v219, v221
	v_cvt_pk_bf16_f32 v153, v220, v222
	v_cvt_pk_bf16_f32 v154, v215, v217
	v_cvt_pk_bf16_f32 v155, v216, v218
	v_mfma_f32_32x32x16_bf16 v[64:79], v[244:247], v[232:235], v[64:79]
	v_fma_f32 v176, v214, v176, v211
	s_waitcnt lgkmcnt(0)
	v_mfma_f32_32x32x16_bf16 v[80:95], v[236:239], v[248:251], v[80:95]
	v_mfma_f32_32x32x16_bf16 v[64:79], v[240:243], v[248:251], v[64:79]
	v_lshl_add_u32 v231, s76, 14, v178
	ds_read_b64_tr_b16 v[232:233], v231 offset:0
	ds_read_b64_tr_b16 v[234:235], v231 offset:2048
	ds_read_b64_tr_b16 v[236:237], v231 offset:512
	ds_read_b64_tr_b16 v[238:239], v231 offset:2560
	ds_read_b64_tr_b16 v[240:241], v231 offset:1024
	ds_read_b64_tr_b16 v[242:243], v231 offset:3072
	ds_read_b64_tr_b16 v[248:249], v231 offset:1536
	ds_read_b64_tr_b16 v[250:251], v231 offset:3584
	ds_read_b64_tr_b16 v[244:245], v231 offset:4096
	ds_read_b64_tr_b16 v[246:247], v231 offset:6144
	s_nop 3
	v_max3_f32 v194, v80, v81, v82
	v_max3_f32 v195, v64, v65, v66
	v_max3_f32 v194, v194, v83, v84
	v_max3_f32 v195, v195, v67, v68
	s_waitcnt lgkmcnt(6)
	v_mfma_f32_32x32x16_bf16 v[32:47], v[148:151], v[232:235], v[32:47]
	ds_read_b64_tr_b16 v[232:233], v231 offset:4608
	ds_read_b64_tr_b16 v[234:235], v231 offset:6656
	v_max3_f32 v194, v194, v85, v86
	v_max3_f32 v195, v195, v69, v70
	v_max3_f32 v194, v194, v87, v88
	v_max3_f32 v195, v195, v71, v72
	v_mfma_f32_32x32x16_bf16 v[48:63], v[148:151], v[236:239], v[48:63]
	ds_read_b64_tr_b16 v[236:237], v231 offset:5120
	ds_read_b64_tr_b16 v[238:239], v231 offset:7168
	v_max3_f32 v194, v194, v89, v90
	v_max3_f32 v195, v195, v73, v74
	v_max3_f32 v194, v194, v91, v92
	v_max3_f32 v195, v195, v75, v76
	s_waitcnt lgkmcnt(6)
	v_mfma_f32_32x32x16_bf16 v[16:31], v[148:151], v[240:243], v[16:31]
	ds_read_b64_tr_b16 v[240:241], v231 offset:5632
	ds_read_b64_tr_b16 v[242:243], v231 offset:7680
	v_max3_f32 v194, v194, v93, v94
	v_max3_f32 v195, v195, v77, v78
	v_max3_f32 v194, v194, v95, v195
	v_max_f32_e32 v194, v194, v79
	v_mfma_f32_32x32x16_bf16 v[0:15], v[148:151], v[248:251], v[0:15]
	ds_read_b64_tr_b16 v[248:249], v231 offset:8192
	ds_read_b64_tr_b16 v[250:251], v231 offset:10240
	v_mov_b32_e32 v195, v194
	s_nop 1
	v_permlane32_swap_b32_e32 v194, v195
	v_max_f32_e32 v194, v194, v195
	s_waitcnt lgkmcnt(6)
	v_mfma_f32_32x32x16_bf16 v[32:47], v[152:155], v[244:247], v[32:47]
	ds_read_b64_tr_b16 v[244:245], v231 offset:8704
	ds_read_b64_tr_b16 v[246:247], v231 offset:10752
	v_sub_f32_e32 v195, v194, v210
	v_cmp_ge_f32_e32 vcc, s15, v195
	v_mfma_f32_32x32x16_bf16 v[48:63], v[152:155], v[232:235], v[48:63]
	ds_read_b64_tr_b16 v[232:233], v231 offset:9216
	ds_read_b64_tr_b16 v[234:235], v231 offset:11264
	s_cmp_eq_u64 vcc, exec
	s_cselect_b64 s[40:41], -1, 0
	s_cbranch_scc1 .Lattn_fast2p
	v_max_f32_e32 v194, v210, v194
	v_sub_f32_e32 v195, v210, v194
	v_mul_f32_e32 v195, 0x3dd53b94, v195
	v_exp_f32_e32 v213, v195
	v_mov_b32_e32 v210, v194
	s_branch .Lattn_join2p

; __device__ __forceinline__ void partialSM(f32x16& p0, f32x16& p1, float& m_reg, float& mn, float& alpha) {
;     ...
;   float mnC = -mn * C;
; #pragma unroll
;   for (int r = 0; r < 16; ++r) p0[r] = fmaf(p0[r], C, mnC);
; #pragma unroll
;   for (int r = 0; r < 16; ++r) p1[r] = fmaf(p1[r], C, mnC);
; template <int D0> __device__ __forceinline__ void pv_one(f32x16& od, int vb, bf16x8 pa0, bf16x8 pa1, bf16x8 pa2, bf16x8 pa3) {
;   const s16x4 l0 = tr_read<v_rd_off(D0, 0, 0)>(vb), h0 = tr_read<v_rd_off(D0, 0, 1)>(vb), l1 = tr_read<v_rd_off(D0, 1, 0)>(vb), h1 = tr_read<v_rd_off(D0, 1, 1)>(vb);
;   const s16x4 l2 = tr_read<v_rd_off(D0, 2, 0)>(vb), h2 = tr_read<v_rd_off(D0, 2, 1)>(vb), l3 = tr_read<v_rd_off(D0, 3, 0)>(vb), h3 = tr_read<v_rd_off(D0, 3, 1)>(vb);
;   asm volatile("s_waitcnt lgkmcnt(0)" ::: "memory"); SBAR();
;     ...
;   od = __builtin_amdgcn_mfma_f32_32x32x16_bf16(pa0, PK(l0, h0), od, 0, 0, 0);
;   od = __builtin_amdgcn_mfma_f32_32x32x16_bf16(pa1, PK(l1, h1), od, 0, 0, 0);
;   od = __builtin_amdgcn_mfma_f32_32x32x16_bf16(pa2, PK(l2, h2), od, 0, 0, 0);
;   od = __builtin_amdgcn_mfma_f32_32x32x16_bf16(pa3, PK(l3, h3), od, 0, 0, 0);
;     ...
; }
; __device__ __forceinline__ void pv_d0(f32x16* o, int vb, bf16x8 pa0, bf16x8 pa1, bf16x8 pa2, bf16x8 pa3) {
;   pv_one<0>(o[0], vb, pa0, pa1, pa2, pa3); pv_one<1>(o[1], vb, pa0, pa1, pa2, pa3); pv_one<2>(o[2], vb, pa0, pa1, pa2, pa3); pv_one<3>(o[3], vb, pa0, pa1, pa2, pa3);
; }
; __device__ __forceinline__ void attn_unit(const bf16_t* __restrict__ Qb, const bf16_t* __restrict__ Kn, const bf16_t* __restrict__ Vh, const bf16_t* __restrict__ Kr,
;                                           bf16_t* GO, int seq, char* lds, const int tid) {
;   const int wid = tid >> 6, lane = tid & 63, r32 = lane & 31, hi = lane >> 5;
;   char* V_lds = lds; char* K_lds = lds + 3 * SHM_V;
;   float* ws = (float*)(lds + 3 * SHM_V + 3 * SHM_K) + wid * 64; float* li_l = ws; float* al_l = ws + 32;
;   if (wid < 4) __builtin_amdgcn_s_setprio(2); else __builtin_amdgcn_s_setprio(0);
;   float m_reg = -1e30f, l_reg = 0; f32x16 o[4] = {}; bf16x8 qr[8];
;   char* qrl = lds + 3 * SHM_V + 3 * SHM_K + NW * 64 * 4 + wid * 4096 + r32 * 128;
;   const bf16_t* Qw = Qb + (long)(wid * QBLK + r32) * LDQ + hi * 8;
; #pragma unroll
;   for (int d0 = 0; d0 < 8; ++d0) qr[d0] = *reinterpret_cast<const bf16x8*>(Qw + d0 * 16);
; #pragma unroll
.Lattn_join2p:
	v_mul_f32_e32 v194, 0xbdd53b94, v210
	s_waitcnt lgkmcnt(6)
	v_mfma_f32_32x32x16_bf16 v[16:31], v[152:155], v[236:239], v[16:31]
	ds_read_b64_tr_b16 v[236:237], v231 offset:9728
	ds_read_b64_tr_b16 v[238:239], v231 offset:11776
	v_fmamk_f32 v225, v80, 0x3dd53b94, v194
	v_fmamk_f32 v228, v81, 0x3dd53b94, v194
	v_fmamk_f32 v226, v82, 0x3dd53b94, v194
	v_fmamk_f32 v229, v83, 0x3dd53b94, v194
	v_mfma_f32_32x32x16_bf16 v[0:15], v[152:155], v[240:243], v[0:15]
	ds_read_b64_tr_b16 v[240:241], v231 offset:12288
	ds_read_b64_tr_b16 v[242:243], v231 offset:14336
	v_fmamk_f32 v150, v76, 0x3dd53b94, v194
	v_fmamk_f32 v151, v77, 0x3dd53b94, v194
	v_fmamk_f32 v148, v78, 0x3dd53b94, v194
	v_fmamk_f32 v149, v79, 0x3dd53b94, v194
	s_waitcnt lgkmcnt(6)
	v_mfma_f32_32x32x16_bf16 v[32:47], v[156:159], v[248:251], v[32:47]
	ds_read_b64_tr_b16 v[248:249], v231 offset:12800
	ds_read_b64_tr_b16 v[250:251], v231 offset:14848
	v_fmamk_f32 v227, v84, 0x3dd53b94, v194
	v_fmamk_f32 v230, v85, 0x3dd53b94, v194
	v_fmamk_f32 v223, v86, 0x3dd53b94, v194
	v_fmamk_f32 v224, v87, 0x3dd53b94, v194
	v_mfma_f32_32x32x16_bf16 v[48:63], v[156:159], v[244:247], v[48:63]
	ds_read_b64_tr_b16 v[244:245], v231 offset:13312
	ds_read_b64_tr_b16 v[246:247], v231 offset:15360
	v_fmamk_f32 v154, v72, 0x3dd53b94, v194
	v_fmamk_f32 v155, v73, 0x3dd53b94, v194
	v_fmamk_f32 v152, v74, 0x3dd53b94, v194
	v_fmamk_f32 v153, v75, 0x3dd53b94, v194
	s_waitcnt lgkmcnt(6)
	v_mfma_f32_32x32x16_bf16 v[16:31], v[156:159], v[232:235], v[16:31]
	ds_read_b64_tr_b16 v[232:233], v231 offset:13824
	ds_read_b64_tr_b16 v[234:235], v231 offset:15872
	v_fmamk_f32 v219, v88, 0x3dd53b94, v194
	v_fmamk_f32 v221, v89, 0x3dd53b94, v194
	v_fmamk_f32 v220, v90, 0x3dd53b94, v194
	v_fmamk_f32 v222, v91, 0x3dd53b94, v194
	v_mfma_f32_32x32x16_bf16 v[0:15], v[156:159], v[236:239], v[0:15]
	v_fmamk_f32 v158, v68, 0x3dd53b94, v194
	v_fmamk_f32 v159, v69, 0x3dd53b94, v194
	v_fmamk_f32 v156, v70, 0x3dd53b94, v194
	v_fmamk_f32 v157, v71, 0x3dd53b94, v194
	s_waitcnt lgkmcnt(0)
	s_barrier
	ds_read_b128 v[236:239], v199 offset:36864
	v_mfma_f32_32x32x16_bf16 v[32:47], v[160:163], v[240:243], v[32:47]
	ds_read_b128 v[240:243], v199 offset:49152
	v_fmamk_f32 v215, v92, 0x3dd53b94, v194
	v_fmamk_f32 v217, v93, 0x3dd53b94, v194
	v_fmamk_f32 v216, v94, 0x3dd53b94, v194
	v_fmamk_f32 v218, v95, 0x3dd53b94, v194
	v_mfma_f32_32x32x16_bf16 v[48:63], v[160:163], v[248:251], v[48:63]
	ds_read_b128 v[248:251], v205 offset:36864
	v_mfma_f32_32x32x16_bf16 v[16:31], v[160:163], v[244:247], v[16:31]
	ds_read_b128 v[244:247], v205 offset:49152
	v_mfma_f32_32x32x16_bf16 v[0:15], v[160:163], v[232:235], v[0:15]
	ds_read_b128 v[232:235], v206 offset:36864
	v_fmamk_f32 v162, v64, 0x3dd53b94, v194
	v_fmamk_f32 v163, v65, 0x3dd53b94, v194
	v_fmamk_f32 v160, v66, 0x3dd53b94, v194
	v_fmamk_f32 v161, v67, 0x3dd53b94, v194
	s_and_b64 vcc, exec, s[40:41]
	s_cbranch_vccnz .Lattn_skip_rs2p
	s_and_saveexec_b64 s[18:19], s[38:39]
	ds_write_b32 v175, v213 offset:128
	s_or_b64 exec, exec, s[18:19]
	s_waitcnt lgkmcnt(0)
	v_add_u32_e32 v194, v173, v164
	ds_read_b128 v[64:67], v194 offset:224
	ds_read_b128 v[68:71], v194 offset:192
	ds_read_b128 v[72:75], v194 offset:160
	ds_read_b128 v[76:79], v194 offset:128
	s_waitcnt lgkmcnt(0)
	v_pk_mul_f32 v[44:45], v[44:45], v[64:65]
	v_pk_mul_f32 v[46:47], v[46:47], v[66:67]
	v_pk_mul_f32 v[40:41], v[40:41], v[68:69]
	v_pk_mul_f32 v[42:43], v[42:43], v[70:71]
	v_pk_mul_f32 v[36:37], v[36:37], v[72:73]
	v_pk_mul_f32 v[38:39], v[38:39], v[74:75]
	v_pk_mul_f32 v[32:33], v[32:33], v[76:77]
	v_pk_mul_f32 v[34:35], v[34:35], v[78:79]
	v_pk_mul_f32 v[60:61], v[60:61], v[64:65]
	v_pk_mul_f32 v[62:63], v[62:63], v[66:67]
	v_pk_mul_f32 v[56:57], v[56:57], v[68:69]
	v_pk_mul_f32 v[58:59], v[58:59], v[70:71]
	v_pk_mul_f32 v[52:53], v[52:53], v[72:73]
	v_pk_mul_f32 v[54:55], v[54:55], v[74:75]
	v_pk_mul_f32 v[48:49], v[48:49], v[76:77]
	v_pk_mul_f32 v[50:51], v[50:51], v[78:79]
	v_pk_mul_f32 v[28:29], v[28:29], v[64:65]
	v_pk_mul_f32 v[30:31], v[30:31], v[66:67]
	v_pk_mul_f32 v[24:25], v[24:25], v[68:69]
	v_pk_mul_f32 v[26:27], v[26:27], v[70:71]
	v_pk_mul_f32 v[20:21], v[20:21], v[72:73]
	v_pk_mul_f32 v[22:23], v[22:23], v[74:75]
	v_pk_mul_f32 v[16:17], v[16:17], v[76:77]
	v_pk_mul_f32 v[18:19], v[18:19], v[78:79]
	v_pk_mul_f32 v[12:13], v[12:13], v[64:65]
	v_pk_mul_f32 v[14:15], v[14:15], v[66:67]
	v_pk_mul_f32 v[8:9], v[8:9], v[68:69]
	v_pk_mul_f32 v[10:11], v[10:11], v[70:71]
	v_pk_mul_f32 v[4:5], v[4:5], v[72:73]
	v_pk_mul_f32 v[6:7], v[6:7], v[74:75]
	v_pk_mul_f32 v[0:1], v[0:1], v[76:77]
	v_pk_mul_f32 v[2:3], v[2:3], v[78:79]

; __device__ __forceinline__ void partialSM(f32x16& p0, f32x16& p1, float& m_reg, float& mn, float& alpha) {
;     ...
;   for (int r = 0; r < 16; ++r) p0[r] = __builtin_amdgcn_exp2f(p0[r]);
; }
; __device__ __forceinline__ void finishSM(f32x16& p0, f32x16& p1, float alpha, float& l_reg, bf16x8& pa0, bf16x8& pa1, bf16x8& pa2, bf16x8& pa3) {
; #pragma unroll
;   for (int r = 0; r < 16; ++r) p1[r] = __builtin_amdgcn_exp2f(p1[r]);
;   float ps = 0;
; #pragma unroll
;   for (int r = 0; r < 16; ++r) ps += p0[r];
; #pragma unroll
;   for (int r = 0; r < 16; ++r) ps += p1[r];
;   { auto rr = __builtin_amdgcn_permlane32_swap(__float_as_uint(ps), __float_as_uint(ps), false, false);
;     ps = __uint_as_float(rr[0]) + __uint_as_float(rr[1]); }
;   l_reg = l_reg * alpha + ps;
;     ...
;   PK4(p0, 0, pa0); PK4(p0, 8, pa1); PK4(p1, 0, pa2); PK4(p1, 8, pa3);
;     ...
; }
; __device__ __forceinline__ void qkt(f32x16& p0, f32x16& p1, const char* Ks, const bf16x8* qr, const char* qrl, int r32, int hi) {
;   p0 = f32x16{}; p1 = f32x16{};
; #pragma unroll
;   for (int d0 = 0; d0 < 8; ++d0) { int cb = (d0 * 16 + hi * 8) * 2;
;     bf16x8 b0 = *reinterpret_cast<const bf16x8*>(Ks + KSWZ(r32, cb));
;     bf16x8 b1 = *reinterpret_cast<const bf16x8*>(Ks + KSWZ(32 + r32, cb));
;     p0 = __builtin_amdgcn_mfma_f32_32x32x16_bf16(b0, qr[d0], p0, 0, 0, 0);
;     p1 = __builtin_amdgcn_mfma_f32_32x32x16_bf16(b1, qr[d0], p1, 0, 0, 0); }
; #pragma unroll
;   for (int d0 = 8; d0 < 12; ++d0) { int cb = (d0 * 16 + hi * 8) * 2;
;     bf16x8 b0 = *reinterpret_cast<const bf16x8*>(Ks + KSWZ(r32, cb));
;     bf16x8 b1 = *reinterpret_cast<const bf16x8*>(Ks + KSWZ(32 + r32, cb));
;     bf16x8 qf = *reinterpret_cast<const bf16x8*>(qrl + (((2 * (d0 - 8) + hi) ^ ((r32 >> 1) & 7)) << 4));
;     p0 = __builtin_amdgcn_mfma_f32_32x32x16_bf16(b0, qf, p0, 0, 0, 0);
;     p1 = __builtin_amdgcn_mfma_f32_32x32x16_bf16(b1, qf, p1, 0, 0, 0); }
; }
.Lattn_steady:
	s_sub_i32 s30, s76, 1
	s_cmp_eq_u32 s76, 0
	s_cselect_b32 s30, 2, s30
	s_add_i32 s18, s76, 1
	s_cmp_lg_u32 s76, 2
	s_cselect_b32 s18, s18, 0
	v_exp_f32_e32 v225, v225
	v_exp_f32_e32 v228, v228
	v_exp_f32_e32 v226, v226
	v_add_f32_e32 v211, v225, v228
	s_waitcnt lgkmcnt(3)
	v_mfma_f32_32x32x16_bf16 v[80:95], v[236:239], v[124:127], 0
	ds_read_b128 v[236:239], v206 offset:49152
	v_exp_f32_e32 v229, v229
	v_add_f32_e32 v211, v226, v211
	v_exp_f32_e32 v227, v227
	v_add_f32_e32 v211, v229, v211
	v_mfma_f32_32x32x16_bf16 v[64:79], v[240:243], v[124:127], 0
	ds_read_b128 v[240:243], v208 offset:36864
	v_exp_f32_e32 v230, v230
	v_add_f32_e32 v211, v227, v211
	v_exp_f32_e32 v223, v223
	v_add_f32_e32 v211, v230, v211
	s_waitcnt lgkmcnt(3)
	v_mfma_f32_32x32x16_bf16 v[80:95], v[248:251], v[120:123], v[80:95]
	ds_read_b128 v[248:251], v208 offset:49152
	v_exp_f32_e32 v224, v224
	v_add_f32_e32 v211, v223, v211
	v_exp_f32_e32 v219, v219
	v_add_f32_e32 v211, v224, v211
	v_mfma_f32_32x32x16_bf16 v[64:79], v[244:247], v[120:123], v[64:79]
	ds_read_b128 v[244:247], v207 offset:36864
	v_exp_f32_e32 v221, v221
	v_add_f32_e32 v211, v219, v211
	v_exp_f32_e32 v220, v220
	v_add_f32_e32 v211, v221, v211
	s_waitcnt lgkmcnt(3)
	v_mfma_f32_32x32x16_bf16 v[80:95], v[232:235], v[116:119], v[80:95]
	ds_read_b128 v[232:235], v207 offset:49152
	v_exp_f32_e32 v222, v222
	v_add_f32_e32 v211, v220, v211
	v_exp_f32_e32 v215, v215
	v_add_f32_e32 v211, v222, v211
	v_mfma_f32_32x32x16_bf16 v[64:79], v[236:239], v[116:119], v[64:79]
	ds_read_b128 v[236:239], v204 offset:36864
	v_exp_f32_e32 v217, v217
	v_add_f32_e32 v211, v215, v211
	v_exp_f32_e32 v216, v216
	v_add_f32_e32 v211, v217, v211
	s_waitcnt lgkmcnt(3)
	v_mfma_f32_32x32x16_bf16 v[80:95], v[240:243], v[112:115], v[80:95]
	ds_read_b128 v[240:243], v204 offset:49152
	v_exp_f32_e32 v218, v218
	v_add_f32_e32 v211, v216, v211
	v_exp_f32_e32 v162, v162
	v_add_f32_e32 v211, v218, v211
	v_mfma_f32_32x32x16_bf16 v[64:79], v[248:251], v[112:115], v[64:79]
	ds_read_b128 v[248:251], v203 offset:36864
	v_exp_f32_e32 v163, v163
	v_exp_f32_e32 v160, v160
	v_exp_f32_e32 v161, v161
	s_waitcnt lgkmcnt(3)
	v_mfma_f32_32x32x16_bf16 v[80:95], v[244:247], v[108:111], v[80:95]
	ds_read_b128 v[244:247], v203 offset:49152
	v_exp_f32_e32 v158, v158
	v_exp_f32_e32 v159, v159
	v_exp_f32_e32 v156, v156
	v_mfma_f32_32x32x16_bf16 v[64:79], v[232:235], v[108:111], v[64:79]
	ds_read_b128 v[232:235], v200 offset:36864
	v_exp_f32_e32 v157, v157
	v_exp_f32_e32 v154, v154
	v_exp_f32_e32 v155, v155
	s_waitcnt lgkmcnt(3)
	v_mfma_f32_32x32x16_bf16 v[80:95], v[236:239], v[104:107], v[80:95]
	ds_read_b128 v[236:239], v200 offset:49152
	v_exp_f32_e32 v152, v152
	v_exp_f32_e32 v153, v153
	v_exp_f32_e32 v150, v150
	v_mfma_f32_32x32x16_bf16 v[64:79], v[240:243], v[104:107], v[64:79]
	ds_read_b128 v[240:243], v191 offset:36864
	v_exp_f32_e32 v151, v151
	v_exp_f32_e32 v148, v148
	v_exp_f32_e32 v149, v149
	s_waitcnt lgkmcnt(3)
	v_mfma_f32_32x32x16_bf16 v[80:95], v[248:251], v[100:103], v[80:95]
	ds_read_b128 v[248:251], v202 offset:49152
	v_add_f32_e32 v212, v162, v163
	v_add_f32_e32 v212, v160, v212
	v_add_f32_e32 v212, v161, v212
	v_add_f32_e32 v212, v158, v212
	v_add_f32_e32 v212, v159, v212
	v_add_f32_e32 v212, v156, v212
	v_mfma_f32_32x32x16_bf16 v[64:79], v[244:247], v[100:103], v[64:79]
	ds_read_b128 v[244:247], v182
	v_add_f32_e32 v212, v157, v212
	v_add_f32_e32 v212, v154, v212
	v_add_f32_e32 v212, v155, v212
	v_add_f32_e32 v212, v152, v212
	v_add_f32_e32 v212, v153, v212
	v_add_f32_e32 v212, v150, v212
	s_waitcnt lgkmcnt(3)
	v_mfma_f32_32x32x16_bf16 v[80:95], v[232:235], v[96:99], v[80:95]
	ds_read_b128 v[232:235], v198 offset:36864
	v_add_f32_e32 v212, v151, v212
	v_add_f32_e32 v212, v148, v212
	v_add_f32_e32 v212, v149, v212
	v_add_f32_e32 v211, v211, v212
	v_mov_b32_e32 v212, v211
	s_lshl_b32 s19, s18, 14
	v_add_u32_e32 v231, s19, v183
	s_waitcnt vmcnt(0)
	v_mfma_f32_32x32x16_bf16 v[64:79], v[236:239], v[96:99], v[64:79]
	ds_read_b128 v[236:239], v201 offset:49152
	ds_write_b128 v231, v[140:143]
	v_add_u32_e32 v140, s19, v184
	ds_write_b128 v140, v[144:147]
	ds_write_b128 v185, v[136:139] offset:12288
	ds_write_b128 v185, v[132:135] offset:24576
	s_mov_b32 s18, 0xfffa0000
	ds_write_b128 v186, v[128:131] offset:12288
	v_add_co_u32_e32 v128, vcc, s18, v168
	s_mov_b32 s18, 0xfffc0000
	s_nop 0
	s_waitcnt lgkmcnt(7)
; __device__ __forceinline__ void finishSM(f32x16& p0, f32x16& p1, float alpha, float& l_reg, bf16x8& pa0, bf16x8& pa1, bf16x8& pa2, bf16x8& pa3) {
;     ...
;   PK4(p0, 0, pa0); PK4(p0, 8, pa1); PK4(p1, 0, pa2); PK4(p1, 8, pa3);
;     ...
; }
; __device__ __forceinline__ void qkt(f32x16& p0, f32x16& p1, const char* Ks, const bf16x8* qr, const char* qrl, int r32, int hi) {
;   p0 = f32x16{}; p1 = f32x16{};
; #pragma unroll
;   for (int d0 = 0; d0 < 8; ++d0) { int cb = (d0 * 16 + hi * 8) * 2;
;     bf16x8 b0 = *reinterpret_cast<const bf16x8*>(Ks + KSWZ(r32, cb));
;     bf16x8 b1 = *reinterpret_cast<const bf16x8*>(Ks + KSWZ(32 + r32, cb));
;     p0 = __builtin_amdgcn_mfma_f32_32x32x16_bf16(b0, qr[d0], p0, 0, 0, 0);
;     p1 = __builtin_amdgcn_mfma_f32_32x32x16_bf16(b1, qr[d0], p1, 0, 0, 0); }
; #pragma unroll
;   for (int d0 = 8; d0 < 12; ++d0) { int cb = (d0 * 16 + hi * 8) * 2;
;     bf16x8 b0 = *reinterpret_cast<const bf16x8*>(Ks + KSWZ(r32, cb));
;     bf16x8 b1 = *reinterpret_cast<const bf16x8*>(Ks + KSWZ(32 + r32, cb));
;     bf16x8 qf = *reinterpret_cast<const bf16x8*>(qrl + (((2 * (d0 - 8) + hi) ^ ((r32 >> 1) & 7)) << 4));
;     p0 = __builtin_amdgcn_mfma_f32_32x32x16_bf16(b0, qf, p0, 0, 0, 0);
;     p1 = __builtin_amdgcn_mfma_f32_32x32x16_bf16(b1, qf, p1, 0, 0, 0); }
; }
; __device__ __forceinline__ int v_st(int k, int c) { const int kk = (k & ~0xC) | ((k & 4) << 1) | ((k & 8) >> 1); return ((kk >> 3) * 4 + (c >> 5)) * 512 + ((kk & 7) * 32 + (c & 31)) * 2; }
; __device__ __forceinline__ int v_rd_base(int lane) { return ((lane & 3) << 3) | (((lane >> 2) & 3) << 6) | (((lane >> 4) & 1) << 5) | (((lane >> 5) & 1) << 8); }
; template <int OFF> __device__ __forceinline__ s16x4 tr_read(int vb) {
;   s16x4 r; asm volatile("ds_read_b64_tr_b16 %0, %1 offset:%2" : "=&v"(r) : "v"(vb), "i"(OFF) : "memory"); return r;
; }
; template <int D0> __device__ __forceinline__ void pv_one(f32x16& od, int vb, bf16x8 pa0, bf16x8 pa1, bf16x8 pa2, bf16x8 pa3) {
;   const s16x4 l0 = tr_read<v_rd_off(D0, 0, 0)>(vb), h0 = tr_read<v_rd_off(D0, 0, 1)>(vb), l1 = tr_read<v_rd_off(D0, 1, 0)>(vb), h1 = tr_read<v_rd_off(D0, 1, 1)>(vb);
;   const s16x4 l2 = tr_read<v_rd_off(D0, 2, 0)>(vb), h2 = tr_read<v_rd_off(D0, 2, 1)>(vb), l3 = tr_read<v_rd_off(D0, 3, 0)>(vb), h3 = tr_read<v_rd_off(D0, 3, 1)>(vb);
;   asm volatile("s_waitcnt lgkmcnt(0)" ::: "memory"); SBAR();
	v_mfma_f32_32x32x16_bf16 v[80:95], v[240:243], v[244:247], v[80:95]
	ds_read_b128 v[240:243], v181
	v_addc_co_u32_e32 v129, vcc, -1, v169, vcc
	v_add_co_u32_e32 v130, vcc, s18, v168
	s_movk_i32 s18, 0xe000
	s_nop 0
	v_addc_co_u32_e32 v131, vcc, -1, v169, vcc
	global_load_dwordx4 v[140:143], v[128:129], off
	global_load_dwordx4 v[136:139], v[128:129], off offset:-256
	global_load_dwordx4 v[144:147], v[130:131], off
	v_mfma_f32_32x32x16_bf16 v[64:79], v[248:251], v[244:247], v[64:79]
	ds_read_b128 v[248:251], v187 offset:36864
	ds_read_b128 v[244:247], v189 offset:49152
	global_load_dwordx4 v[132:135], v[130:131], off offset:-256
	v_add_co_u32_e32 v128, vcc, s18, v166
	s_nop 1
	v_addc_co_u32_e32 v129, vcc, -1, v167, vcc
	global_load_dwordx4 v[128:131], v[128:129], off
	v_cvt_pk_bf16_f32 v158, v158, v159
	v_cvt_pk_bf16_f32 v159, v156, v157
	s_waitcnt lgkmcnt(2)
	v_mfma_f32_32x32x16_bf16 v[80:95], v[232:235], v[240:243], v[80:95]
	ds_read_b128 v[232:235], v179
	v_permlane32_swap_b32_e32 v211, v212
	v_cvt_pk_bf16_f32 v156, v162, v163
	v_cvt_pk_bf16_f32 v157, v160, v161
	v_cvt_pk_bf16_f32 v160, v154, v155
	v_cvt_pk_bf16_f32 v161, v152, v153
	v_cvt_pk_bf16_f32 v162, v150, v151
	v_mfma_f32_32x32x16_bf16 v[64:79], v[236:239], v[240:243], v[64:79]
	ds_read_b128 v[236:239], v188 offset:36864
	ds_read_b128 v[240:243], v190 offset:49152
	v_cvt_pk_bf16_f32 v163, v148, v149
	v_add_f32_e32 v211, v211, v212
	v_cvt_pk_bf16_f32 v148, v225, v228
	v_cvt_pk_bf16_f32 v149, v226, v229
	v_cvt_pk_bf16_f32 v150, v227, v230
	v_cvt_pk_bf16_f32 v151, v223, v224
	s_waitcnt lgkmcnt(2)
	v_mfma_f32_32x32x16_bf16 v[80:95], v[248:251], v[232:235], v[80:95]
	ds_read_b128 v[248:251], v177
	v_cvt_pk_bf16_f32 v152, v219, v221
	v_cvt_pk_bf16_f32 v153, v220, v222
	v_cvt_pk_bf16_f32 v154, v215, v217
	v_cvt_pk_bf16_f32 v155, v216, v218
	v_fma_f32 v176, v209, v176, v211
	v_mfma_f32_32x32x16_bf16 v[64:79], v[244:247], v[232:235], v[64:79]
	s_waitcnt lgkmcnt(0)
	v_mfma_f32_32x32x16_bf16 v[80:95], v[236:239], v[248:251], v[80:95]
	v_mfma_f32_32x32x16_bf16 v[64:79], v[240:243], v[248:251], v[64:79]
	s_lshl_b32 s31, s30, 14
	v_add_u32_e32 v180, s31, v178
	ds_read_b64_tr_b16 v[232:233], v180 offset:0
	ds_read_b64_tr_b16 v[234:235], v180 offset:2048
	ds_read_b64_tr_b16 v[236:237], v180 offset:512
	ds_read_b64_tr_b16 v[238:239], v180 offset:2560
	ds_read_b64_tr_b16 v[240:241], v180 offset:1024
	ds_read_b64_tr_b16 v[242:243], v180 offset:3072
	ds_read_b64_tr_b16 v[248:249], v180 offset:1536
	ds_read_b64_tr_b16 v[250:251], v180 offset:3584
	ds_read_b64_tr_b16 v[244:245], v180 offset:4096
	ds_read_b64_tr_b16 v[246:247], v180 offset:6144
	s_nop 3
	v_max3_f32 v194, v80, v81, v82
	v_max3_f32 v195, v64, v65, v66
	v_max3_f32 v194, v194, v83, v84
	v_max3_f32 v195, v195, v67, v68
	s_waitcnt lgkmcnt(6)
	v_mfma_f32_32x32x16_bf16 v[32:47], v[148:151], v[232:235], v[32:47]
	ds_read_b64_tr_b16 v[232:233], v180 offset:4608
	ds_read_b64_tr_b16 v[234:235], v180 offset:6656
	v_max3_f32 v194, v194, v85, v86
	v_max3_f32 v195, v195, v69, v70
	v_max3_f32 v194, v194, v87, v88
	v_max3_f32 v195, v195, v71, v72
	v_mfma_f32_32x32x16_bf16 v[48:63], v[148:151], v[236:239], v[48:63]
	ds_read_b64_tr_b16 v[236:237], v180 offset:5120
	ds_read_b64_tr_b16 v[238:239], v180 offset:7168
	v_max3_f32 v194, v194, v89, v90
	v_max3_f32 v195, v195, v73, v74
	v_max3_f32 v194, v194, v91, v92
	v_max3_f32 v195, v195, v75, v76
	s_waitcnt lgkmcnt(6)
	v_mfma_f32_32x32x16_bf16 v[16:31], v[148:151], v[240:243], v[16:31]
	ds_read_b64_tr_b16 v[240:241], v180 offset:5632
	ds_read_b64_tr_b16 v[242:243], v180 offset:7680
	v_max3_f32 v194, v194, v93, v94
	v_max3_f32 v195, v195, v77, v78
	v_max3_f32 v194, v194, v95, v195
	v_max_f32_e32 v194, v194, v79
	v_mfma_f32_32x32x16_bf16 v[0:15], v[148:151], v[248:251], v[0:15]
	ds_read_b64_tr_b16 v[248:249], v180 offset:8192
	ds_read_b64_tr_b16 v[250:251], v180 offset:10240
	v_mov_b32_e32 v195, v194
	s_nop 1
	v_permlane32_swap_b32_e32 v194, v195
	v_max_f32_e32 v194, v194, v195
	s_waitcnt lgkmcnt(6)
	v_mfma_f32_32x32x16_bf16 v[32:47], v[152:155], v[244:247], v[32:47]
	ds_read_b64_tr_b16 v[244:245], v180 offset:8704
	ds_read_b64_tr_b16 v[246:247], v180 offset:10752
	v_sub_f32_e32 v195, v194, v210
	v_cmp_ge_f32_e32 vcc, s15, v195
	v_mfma_f32_32x32x16_bf16 v[48:63], v[152:155], v[232:235], v[48:63]
	ds_read_b64_tr_b16 v[232:233], v180 offset:9216
	ds_read_b64_tr_b16 v[234:235], v180 offset:11264
	s_cmp_eq_u64 vcc, exec
	s_cselect_b64 s[40:41], -1, 0
	s_cbranch_scc1 .Lattn_fast1
	v_max_f32_e32 v194, v210, v194
	v_sub_f32_e32 v195, v210, v194
	v_mul_f32_e32 v195, 0x3dd53b94, v195
	v_exp_f32_e32 v214, v195
	v_mov_b32_e32 v210, v194
	s_branch .Lattn_join1

; #define PH_NEXT do { ++k; if (k > lo && k < hi) { xcd_barrier(xbar, wave == 0 && MK_LANE() == 0); } } while (0)
; __global__ void __launch_bounds__(NTHR, 2) mk_fwd(Params Punused) {
;     ...
;             }
;             PH_NEXT;
.LBB0_1169:
	v_mov_b32_e32 v244, 0x358637bd
	v_mov_b32_e32 v245, 1
	v_mbcnt_lo_u32_b32 v246, -1, 0
	v_mbcnt_hi_u32_b32 v246, -1, v246
	v_mov_b32_e32 v247, 0xfff
	v_readlane_b32 s18, v255, 41
	s_add_i32 s20, s18, 3
	v_readlane_b32 s18, v254, 0
	s_cmp_gt_i32 s20, s18
	v_readlane_b32 s21, v254, 1
	s_cselect_b64 s[18:19], -1, 0
	s_cmp_lt_i32 s20, s21
	s_cselect_b64 s[22:23], -1, 0
	s_and_b64 s[18:19], s[18:19], s[22:23]
	s_andn2_b64 vcc, exec, s[18:19]
	s_cbranch_vccnz .LBB0_1217
	s_and_b64 vcc, exec, s[36:37]
	s_mov_b64 s[18:19], 0
	s_cbranch_vccnz .LBB0_1172
	v_mbcnt_lo_u32_b32 v0, -1, 0
	v_mbcnt_hi_u32_b32 v0, -1, v0
	s_nop 0
	v_cmp_eq_u32_e32 vcc, 0, v0
	s_and_b64 s[18:19], vcc, exec
